# RWKV per-chunk loads re-mapped so every load slot has one role per wave (r, k, w-lora, a-lora, v): COMMIT is straight-line instead of five divergent if/else ladders
# speedup vs baseline: 1.0117x; 1.0045x over previous
.LBB0_421:
	s_or_b64 exec, exec, s[18:19]
	s_mul_i32 s52, s36, 0x20800
	s_xor_b64 s[76:77], s[22:23], -1
	s_lshl_b64 s[18:19], s[52:53], 2
	s_add_u32 s18, s20, s18
	v_mov_b32_e32 v6, 0xc200
	v_mov_b32_e32 v7, 0xb000
	s_addc_u32 s19, s21, s19
	v_cndmask_b32_e64 v6, v6, v7, s[16:17]
	s_lshl_b32 s16, s34, 1
	s_add_u32 s20, s20, s16
	s_addc_u32 s21, s21, 0
	s_lshl_b32 s22, s35, 2
	s_add_u32 s18, s18, s22
	s_addc_u32 s19, s19, 0
	s_add_u32 s78, s18, 0x118000
	v_readlane_b32 s18, v255, 3
	v_lshlrev_b32_e32 v4, 1, v116
	s_addc_u32 s79, s19, 0
	v_lshl_add_u32 v61, v235, 2, s18
	s_lshl_b32 s18, s37, 1
	v_and_b32_e32 v5, 14, v4
	v_lshrrev_b32_e32 v7, 2, v116
	s_add_u32 s18, s20, s18
	v_and_b32_e32 v52, 16, v7
	s_addc_u32 s19, s21, 0
	v_lshlrev_b32_e32 v16, 1, v5
	v_ashrrev_i32_e32 v87, 4, v116
	v_add_u32_e32 v64, 0, v4
	v_lshlrev_b32_e32 v67, 5, v5
	v_lshl_add_u64 v[4:5], s[18:19], 0, v[16:17]
	v_lshlrev_b32_e32 v16, 8, v52
	v_lshl_or_b32 v69, v139, 10, v16
	v_lshl_or_b32 v16, v87, 8, v122
	v_add_u32_e32 v92, 16, v87
	v_and_b32_e32 v60, 1, v116
	v_add_u32_e32 v91, 0, v16
	v_lshl_or_b32 v16, v92, 8, v122
	v_add_u32_e32 v93, 0, v16
	v_add_u32_e32 v16, 0x11200, v64
	v_cmp_eq_u32_e32 vcc, 0, v60
	v_or_b32_e32 v7, v52, v140
	v_mul_u32_u24_e32 v7, 0x90, v7
	v_cndmask_b32_e32 v98, v61, v16, vcc
	v_add_u32_e32 v16, 0x11000, v64
	v_cndmask_b32_e32 v99, v61, v16, vcc
	v_add_u32_e32 v16, 0x10e00, v64
	v_cndmask_b32_e32 v100, v61, v16, vcc
	v_add_u32_e32 v16, 0x10c00, v64
	v_cndmask_b32_e32 v101, v61, v16, vcc
	v_add_u32_e32 v16, 0x10a00, v64
	s_mov_b64 s[18:19], 0xe488000
	v_cndmask_b32_e32 v102, v61, v16, vcc
	v_add_u32_e32 v16, 0x10800, v64
	v_add3_u32 v62, 0, v6, v7
	v_or_b32_e32 v6, s38, v140
	v_lshl_add_u64 v[18:19], v[4:5], 0, s[18:19]
	s_mov_b32 s18, 0x5040100
	s_movk_i32 s20, 0xffde
	v_add_u32_e32 v97, v106, v105
	v_cndmask_b32_e32 v103, v61, v16, vcc
	v_add_u32_e32 v16, 0x10600, v64
	v_cmp_eq_u32_e64 s[16:17], 0, v6
	v_perm_b32 v7, v153, v151, s18
	v_perm_b32 v6, v149, v147, s18
	v_perm_b32 v5, v145, v143, s18
	v_perm_b32 v4, v142, v141, s18
	v_perm_b32 v11, v165, v163, s18
	v_perm_b32 v10, v162, v161, s18
	v_perm_b32 v9, v160, v159, s18
	v_perm_b32 v8, v158, v157, s18
	v_perm_b32 v15, v186, v184, s18
	v_perm_b32 v14, v182, v180, s18
	v_perm_b32 v13, v178, v176, s18
	v_perm_b32 v12, v174, v173, s18
	v_perm_b32 v27, v198, v195, s18
	v_perm_b32 v26, v194, v193, s18
	v_perm_b32 v25, v192, v191, s18
	v_perm_b32 v24, v190, v189, s18
	v_perm_b32 v35, v156, v155, s18
	v_perm_b32 v34, v154, v152, s18
	v_perm_b32 v33, v150, v148, s18
	v_perm_b32 v32, v146, v144, s18
	v_perm_b32 v39, v172, v171, s18
	v_perm_b32 v38, v170, v169, s18
	v_perm_b32 v37, v168, v167, s18
	v_perm_b32 v36, v166, v164, s18
	v_perm_b32 v43, v188, v187, s18
	v_perm_b32 v42, v185, v183, s18
	v_perm_b32 v41, v181, v179, s18
	v_perm_b32 v40, v177, v175, s18
	v_perm_b32 v47, v204, v203, s18
	v_perm_b32 v46, v202, v201, s18
	v_perm_b32 v45, v200, v199, s18
	v_perm_b32 v44, v197, v196, s18
	v_mad_u64_u32 v[58:59], s[18:19], v97, s20, v[104:105]
	v_cndmask_b32_e32 v104, v61, v16, vcc
	v_add_u32_e32 v16, 0x10400, v64
	v_cndmask_b32_e32 v105, v61, v16, vcc
	v_add_u32_e32 v16, 0x10200, v64
	v_cndmask_b32_e32 v106, v61, v16, vcc
	v_add_u32_e32 v16, 0x10000, v64
	v_cndmask_b32_e32 v107, v61, v16, vcc
	v_add_u32_e32 v16, 0xfe00, v64
	v_cndmask_b32_e32 v108, v61, v16, vcc
	v_add_u32_e32 v16, 0xfc00, v64
	v_cndmask_b32_e32 v109, v61, v16, vcc
	v_add_u32_e32 v16, 0xfa00, v64
	v_cndmask_b32_e32 v110, v61, v16, vcc
	v_add_u32_e32 v16, 0xf800, v64
	v_cndmask_b32_e32 v111, v61, v16, vcc
	v_add_u32_e32 v16, 0xf600, v64
	v_cndmask_b32_e32 v112, v61, v16, vcc
	v_add_u32_e32 v16, 0xf400, v64
	v_cndmask_b32_e32 v113, v61, v16, vcc
	v_add_u32_e32 v16, 0xf200, v64
	v_cndmask_b32_e32 v114, v61, v16, vcc
	v_add_u32_e32 v16, 0xf000, v64
	v_add_u32_e32 v94, v206, v205
	v_cndmask_b32_e32 v115, v61, v16, vcc
	v_add_u32_e32 v16, 0xee00, v64
	v_and_b32_e32 v63, 48, v116
	v_ashrrev_i32_e32 v90, 3, v116
	v_mad_u64_u32 v[52:53], s[18:19], v94, s20, v[116:117]
	v_cndmask_b32_e32 v116, v61, v16, vcc
	v_add_u32_e32 v16, 0xec00, v64
	v_add_u32_e32 v95, v234, v233
	v_cndmask_b32_e32 v122, v61, v16, vcc
	v_add_u32_e32 v16, 0xea00, v64
	v_mad_u64_u32 v[54:55], s[18:19], v95, s20, v[124:125]
	v_add_u32_e32 v96, v237, v236
	v_cndmask_b32_e32 v124, v61, v16, vcc
	v_add_u32_e32 v16, 0xe800, v64
	v_mad_u64_u32 v[56:57], s[18:19], v96, s20, v[126:127]
	v_cndmask_b32_e32 v126, v61, v16, vcc
	v_add_u32_e32 v16, 0xe600, v64
	v_lshl_add_u32 v88, v140, 4, 0
	v_cndmask_b32_e32 v139, v61, v16, vcc
	v_add_u32_e32 v16, 0xe400, v64
	v_mad_i32_i24 v68, v140, -12, v88
	v_cndmask_b32_e32 v140, v61, v16, vcc
	v_add_u32_e32 v16, 0xe200, v64
	v_cndmask_b32_e32 v141, v61, v16, vcc
	v_add_u32_e32 v16, 0xe000, v64
	v_cndmask_b32_e32 v142, v61, v16, vcc
	v_add_u32_e32 v16, 0xde00, v64
	v_cndmask_b32_e32 v143, v61, v16, vcc
	v_add_u32_e32 v16, 0xdc00, v64
	v_cndmask_b32_e32 v144, v61, v16, vcc
	v_add_u32_e32 v16, 0xda00, v64
	v_cndmask_b32_e32 v145, v61, v16, vcc
	v_add_u32_e32 v16, 0xd800, v64
	v_cndmask_b32_e32 v146, v61, v16, vcc
	v_add_u32_e32 v16, 0xd600, v64
	v_cndmask_b32_e32 v147, v61, v16, vcc
	v_and_b32_e32 v16, -16, v52
	v_add_u32_e32 v65, 0xd400, v64
	v_cmp_ne_u32_e64 s[18:19], 16, v16
	v_lshl_add_u32 v16, v94, 6, 0
	v_lshlrev_b32_e32 v53, 5, v52
	s_mov_b32 s28, 0x9c00
	s_movk_i32 s29, 0xc0
	s_movk_i32 s30, 0xff90
	v_cndmask_b32_e32 v148, v61, v65, vcc
	v_add3_u32 v55, v16, v53, s28
	v_mad_u64_u32 v[60:61], s[20:21], v94, s29, v[16:17]
	v_mul_lo_u32 v16, v94, s30
	v_lshlrev_b32_e32 v59, 4, v52
	v_add3_u32 v59, v60, v16, v59
	v_and_b32_e32 v16, -16, v54
	v_cmp_ne_u32_e64 s[20:21], 16, v16
	v_lshl_add_u32 v16, v95, 6, 0
	v_add_u32_e32 v53, v60, v53
	v_lshlrev_b32_e32 v64, 5, v54
	v_mad_u64_u32 v[60:61], s[22:23], v95, s29, v[16:17]
	v_add3_u32 v65, v16, v64, s28
	v_mul_lo_u32 v16, v95, s30
	v_lshlrev_b32_e32 v61, 4, v54
	v_add3_u32 v71, v60, v16, v61
	v_and_b32_e32 v16, -16, v56
	v_cmp_ne_u32_e64 s[22:23], 16, v16
	v_lshl_add_u32 v16, v96, 6, 0
	v_add_u32_e32 v64, v60, v64
	v_lshlrev_b32_e32 v72, 5, v56
	v_mad_u64_u32 v[60:61], s[24:25], v96, s29, v[16:17]
	v_add3_u32 v82, v16, v72, s28
	v_mul_lo_u32 v16, v96, s30
	v_lshlrev_b32_e32 v61, 4, v56
	v_add3_u32 v158, v60, v16, v61
	v_and_b32_e32 v16, -16, v58
	v_cmp_ne_u32_e64 s[24:25], 16, v16
	v_lshl_add_u32 v16, v97, 6, 0
	v_add_u32_e32 v83, v60, v72
	v_lshlrev_b32_e32 v72, 5, v58
	v_mad_u64_u32 v[60:61], s[26:27], v97, s29, v[16:17]
	v_add3_u32 v152, v16, v72, s28
	v_mul_lo_u32 v16, v97, s30
	v_lshlrev_b32_e32 v61, 4, v58
	v_add3_u32 v159, v60, v16, v61
	v_lshl_add_u32 v16, v86, 6, 0
	v_add_u32_e32 v153, v60, v72
	v_lshlrev_b32_e32 v72, 5, v84
	v_mad_u64_u32 v[60:61], s[26:27], v86, s29, v[16:17]
	v_add3_u32 v155, v16, v72, s28
	v_add_u32_e32 v16, v60, v72
	v_mul_lo_u32 v61, v86, s30
	v_lshlrev_b32_e32 v72, 4, v84
	v_mov_b32_e32 v149, s40
	v_mov_b32_e32 v150, s41
	v_cmp_gt_u32_e64 s[26:27], 32, v52
	v_add3_u32 v160, v60, v61, v72
	v_mov_b32_e32 v80, s42
	v_mov_b32_e32 v81, s34
	v_cmp_gt_i32_e32 vcc, 8, v52
	v_cndmask_b32_e64 v61, v149, v150, s[26:27]
	v_mov_b32_e32 v151, s39
	v_cmp_gt_u32_e64 s[26:27], 24, v52
	v_cndmask_b32_e32 v60, v80, v81, vcc
	v_cmp_gt_i32_e64 s[28:29], 16, v52
	v_cndmask_b32_e64 v61, v61, v151, s[26:27]
	v_cmp_gt_u32_e64 s[30:31], 32, v54
	v_cndmask_b32_e64 v60, v61, v60, s[28:29]
	v_lshl_add_u32 v60, v52, 3, v60
	v_ashrrev_i32_e32 v61, 31, v60
	v_lshl_add_u64 v[72:73], v[60:61], 1, s[58:59]
	v_cmp_gt_i32_e64 s[28:29], 8, v54
	v_cndmask_b32_e64 v61, v149, v150, s[30:31]
	v_cmp_gt_u32_e64 s[30:31], 24, v54
	v_cndmask_b32_e64 v60, v80, v81, s[28:29]
	v_cmp_gt_i32_e64 s[34:35], 16, v54
	v_cndmask_b32_e64 v61, v61, v151, s[30:31]
	v_cmp_gt_u32_e64 s[36:37], 32, v56
	v_cndmask_b32_e64 v60, v61, v60, s[34:35]
	v_lshl_add_u32 v60, v54, 3, v60
	v_ashrrev_i32_e32 v61, 31, v60
	v_lshl_add_u64 v[74:75], v[60:61], 1, s[58:59]
	v_cmp_gt_i32_e64 s[34:35], 8, v56
	v_cndmask_b32_e64 v61, v149, v150, s[36:37]
	v_cmp_gt_u32_e64 s[36:37], 24, v56
	v_cndmask_b32_e64 v60, v80, v81, s[34:35]
	v_cmp_gt_i32_e64 s[38:39], 16, v56
	v_cndmask_b32_e64 v61, v61, v151, s[36:37]
	v_cmp_gt_u32_e64 s[40:41], 32, v58
	v_cndmask_b32_e64 v60, v61, v60, s[38:39]
	v_lshl_add_u32 v60, v56, 3, v60
	v_ashrrev_i32_e32 v61, 31, v60
	v_lshl_add_u64 v[76:77], v[60:61], 1, s[58:59]
	v_cmp_gt_i32_e64 s[38:39], 8, v58
	v_cndmask_b32_e64 v61, v149, v150, s[40:41]
	v_cmp_gt_u32_e64 s[40:41], 24, v58
	v_cndmask_b32_e64 v60, v80, v81, s[38:39]
	v_cmp_gt_i32_e64 s[42:43], 16, v58
	v_cndmask_b32_e64 v61, v61, v151, s[40:41]
	v_cmp_gt_u32_e64 s[44:45], 32, v84
	v_cndmask_b32_e64 v60, v61, v60, s[42:43]
	v_lshl_add_u32 v60, v58, 3, v60
	v_ashrrev_i32_e32 v61, 31, v60
	v_lshl_add_u64 v[78:79], v[60:61], 1, s[58:59]
	v_cmp_gt_i32_e64 s[42:43], 8, v84
	v_cndmask_b32_e64 v61, v149, v150, s[44:45]
	v_cmp_gt_u32_e64 s[44:45], 24, v84
	v_cndmask_b32_e64 v60, v80, v81, s[42:43]
	v_cmp_gt_i32_e64 s[48:49], 16, v84
	v_cndmask_b32_e64 v61, v61, v151, s[44:45]
	v_add_u32_e32 v57, 0x1f00, v53
	v_cndmask_b32_e64 v60, v61, v60, s[48:49]
	v_cmp_gt_u32_e64 s[48:49], 16, v52
	v_add_u32_e32 v70, 0x1f00, v64
	v_add_u32_e32 v85, 0x1f00, v83
	v_cndmask_b32_e64 v52, v55, v57, s[48:49]
	v_cndmask_b32_e32 v149, v52, v53, vcc
	v_cmp_gt_u32_e32 vcc, 16, v54
	v_add_u32_e32 v154, 0x1f00, v153
	v_add_u32_e32 v156, 0x1f00, v16
	v_cndmask_b32_e32 v53, v65, v70, vcc
	v_cmp_gt_u32_e32 vcc, 16, v56
	v_lshl_add_u32 v60, v84, 3, v60
	v_mov_b32_e32 v57, 0xc080
	v_cndmask_b32_e32 v54, v82, v85, vcc
	v_cmp_gt_u32_e32 vcc, 16, v58
	v_lshl_add_u32 v66, v90, 9, 0
	v_ashrrev_i32_e32 v61, 31, v60
	v_cndmask_b32_e32 v55, v152, v154, vcc
	v_cmp_gt_u32_e32 vcc, 16, v84
	v_cndmask_b32_e64 v52, v57, v254, s[26:27]
	v_cndmask_b32_e64 v150, v53, v64, s[28:29]
	v_cndmask_b32_e32 v56, v155, v156, vcc
	v_cndmask_b32_e64 v53, v57, v254, s[30:31]
	v_cndmask_b32_e64 v151, v54, v83, s[34:35]
	v_cndmask_b32_e64 v54, v57, v254, s[36:37]
	v_cndmask_b32_e64 v152, v55, v153, s[38:39]
	v_cndmask_b32_e64 v55, v57, v254, s[40:41]
	v_cndmask_b32_e64 v153, v56, v16, s[42:43]
	v_cndmask_b32_e64 v56, v57, v254, s[44:45]
	v_mov_b32_e32 v16, v17
	v_lshl_add_u32 v89, v87, 2, 0
	v_lshl_add_u64 v[80:81], v[60:61], 1, s[58:59]
	s_mov_b32 s34, -8
	v_add_u32_e32 v154, v62, v63
	v_add_u32_e32 v155, v66, v67
	v_add_u32_e32 v156, v59, v52
	v_add_u32_e32 v157, v71, v53
	v_add_u32_e32 v158, v158, v54
	v_add_u32_e32 v159, v159, v55
	v_add_u32_e32 v160, v160, v56
	v_add_u32_e32 v161, v68, v69
	v_mov_b64_e32 v[82:83], v[16:17]
	v_mov_b64_e32 v[84:85], v[16:17]
	v_mov_b32_e32 v52, v232
	v_mov_b32_e32 v53, v231
	v_mov_b32_e32 v54, v230
	v_mov_b32_e32 v55, v207
	s_waitcnt lgkmcnt(0)
	s_barrier
	v_mad_u64_u32 v[218:219], s[26:27], v94, s83, v[72:73]
	v_mad_u64_u32 v[220:221], s[26:27], v95, s83, v[74:75]
	v_mad_u64_u32 v[222:223], s[26:27], v96, s83, v[76:77]
	v_mad_u64_u32 v[244:245], s[26:27], v97, s83, v[78:79]
	v_mad_u64_u32 v[246:247], s[26:27], v86, s83, v[80:81]
	v_and_b32_e32 v98, 31, v119
	v_lshlrev_b32_e32 v98, 3, v98
	v_lshrrev_b32_e32 v99, 5, v119
	s_lshl_b32 s26, s32, 3
	v_add_u32_e32 v99, s26, v99
	v_lshl_add_u32 v99, v99, 2, v228
	v_add_u32_e32 v99, 0x6000, v99
	v_lshrrev_b32_e32 v100, 1, v119
	v_lshlrev_b32_e32 v100, 2, v100
	v_add_u32_e32 v100, 0xd400, v100
	v_lshrrev_b32_e32 v101, 3, v119
	v_lshlrev_b32_e32 v101, 9, v101
	v_and_b32_e32 v102, 7, v119
	v_lshl_add_u32 v101, v102, 6, v101
	v_add_u32_e32 v101, 0xd400, v101
	v_sub_u32_e32 v102, s26, v102
	v_lshlrev_b32_e32 v102, 1, v102
	v_ashrrev_i32_e32 v103, 31, v102
	v_lshl_add_u64 v[102:103], v[18:19], 0, v[102:103]
	s_load_dwordx2 s[26:27], s[84:85], 0x120
	v_lshrrev_b32_e32 v60, 3, v119
	v_and_b32_e32 v61, 7, v119
	v_mov_b32_e32 v62, s82
	v_add_u32_e32 v62, 0xffffff80, v62
	v_bfe_u32 v63, v62, 2, 3
	v_lshlrev_b32_e32 v63, 6, v63
	v_lshrrev_b32_e32 v64, 5, v62
	v_lshlrev_b32_e32 v64, 6, v64
	v_and_b32_e32 v65, 3, v62
	v_lshlrev_b32_e32 v65, 4, v65
	v_lshl_add_u32 v66, v61, 3, v63
	v_lshl_add_u32 v67, v61, 3, v64
	v_add_u32_e32 v67, 0x600, v67
	v_and_b32_e32 v68, 1, v119
	v_lshl_add_u32 v69, v68, 3, v63
	v_add_u32_e32 v69, v69, v65
	v_add_u32_e32 v69, 0x400, v69
	v_mul_u32_u24_e32 v70, 0x1200, v60
	v_lshrrev_b32_e32 v71, 1, v119
	v_mul_u32_u24_e32 v162, 0x1200, v71
	s_waitcnt lgkmcnt(0)
	s_add_u32 s26, s26, 0x6aa8000
	s_addc_u32 s27, s27, 0
	v_lshl_add_u32 v16, v66, 1, v70
	v_lshl_add_u64 v[218:219], v[16:17], 0, s[26:27]
	v_add_u32_e32 v16, 0x400, v16
	v_lshl_add_u64 v[220:221], v[16:17], 0, s[26:27]
	v_lshl_add_u32 v16, v67, 1, v70
	v_lshl_add_u64 v[222:223], v[16:17], 0, s[26:27]
	v_add_u32_e32 v16, 0x100, v16
	v_lshl_add_u64 v[244:245], v[16:17], 0, s[26:27]
	v_lshl_add_u32 v16, v69, 1, v162
	v_lshl_add_u64 v[246:247], v[16:17], 0, s[26:27]
	v_lshlrev_b32_e32 v149, 8, v60
	v_lshl_add_u32 v149, v61, 5, v149
	v_add_u32_e32 v150, 0x2000, v149
	v_mul_u32_u24_e32 v156, 0x90, v60
	v_lshl_add_u32 v156, v61, 4, v156
	v_add_u32_e32 v156, 0xb000, v156
	v_add_u32_e32 v157, 0x1200, v156
	v_lshlrev_b32_e32 v151, 6, v71
	v_lshl_add_u32 v151, v68, 5, v151
	v_add_u32_e32 v151, 0xa000, v151
	s_branch .LBB0_424

.Lrs_post:
	v_mov_b64_e32 v[56:57], v[82:83]
	s_waitcnt lgkmcnt(0)
	s_barrier
	ds_read_b128 v[60:63], v101
	ds_read_b128 v[64:67], v101 offset:16
	ds_read_b128 v[68:71], v101 offset:32
	ds_read_b128 v[162:165], v101 offset:48
	v_add_u32_e32 v170, s35, v90
	v_ashrrev_i32_e32 v171, 31, v170
	v_lshlrev_b64 v[170:171], 10, v[170:171]
	v_lshl_add_u64 v[170:171], v[102:103], 0, v[170:171]
	s_waitcnt lgkmcnt(2)
	v_add_f32_e32 v60, v60, v61
	v_add_f32_e32 v62, v62, v63
	v_add_f32_e32 v64, v64, v65
	v_add_f32_e32 v66, v66, v67
	v_add_f32_e32 v60, v60, v62
	v_add_f32_e32 v64, v64, v66
	s_waitcnt lgkmcnt(0)
	v_add_f32_e32 v68, v68, v69
	v_add_f32_e32 v70, v70, v71
	v_add_f32_e32 v162, v162, v163
	v_add_f32_e32 v164, v164, v165
	v_add_f32_e32 v68, v68, v70
	v_add_f32_e32 v162, v162, v164
	v_add_f32_e32 v60, v60, v64
	v_add_f32_e32 v68, v68, v162
	v_add_f32_e32 v60, v60, v68
	s_nop 1
	v_mov_b32_dpp v61, v60 quad_perm:[1,0,3,2] row_mask:0xf bank_mask:0xf bound_ctrl:1
	s_nop 0
	v_cvt_pk_bf16_f32 v16, v60, v61
	s_mov_b32 s26, 0x55555555
	s_mov_b32 s27, 0x55555555
	s_and_b64 exec, exec, s[26:27]
	global_atomic_pk_add_bf16 v[170:171], v16, off
	s_mov_b64 exec, -1
	s_andn2_b64 vcc, exec, s[28:29]
	s_cbranch_vccnz .LBB0_423
	s_waitcnt vmcnt(1)
	v_lshlrev_b32_e32 v60, 16, v20
	v_and_b32_e32 v61, 0xffff0000, v20
	v_lshlrev_b32_e32 v62, 16, v21
	v_and_b32_e32 v63, 0xffff0000, v21
	v_lshlrev_b32_e32 v64, 16, v22
	v_and_b32_e32 v65, 0xffff0000, v22
	v_lshlrev_b32_e32 v66, 16, v23
	v_and_b32_e32 v67, 0xffff0000, v23
	ds_write_b128 v149, v[60:63]
	ds_write_b128 v149, v[64:67] offset:16
	v_lshlrev_b32_e32 v162, 16, v52
	v_and_b32_e32 v163, 0xffff0000, v52
	v_lshlrev_b32_e32 v164, 16, v53
	v_and_b32_e32 v165, 0xffff0000, v53
	v_lshlrev_b32_e32 v166, 16, v54
	v_and_b32_e32 v167, 0xffff0000, v54
	v_lshlrev_b32_e32 v168, 16, v55
	v_and_b32_e32 v169, 0xffff0000, v55
	ds_write_b128 v150, v[162:165]
	ds_write_b128 v150, v[166:169] offset:16
	ds_write_b128 v156, v[28:31]
	ds_write_b128 v157, v[0:3]
	s_and_saveexec_b64 s[26:27], s[14:15]
	s_cbranch_execz .Lrc_skip
	v_lshlrev_b32_e32 v60, 16, v48
	v_and_b32_e32 v61, 0xffff0000, v48
	v_lshlrev_b32_e32 v62, 16, v49
	v_and_b32_e32 v63, 0xffff0000, v49
	v_lshlrev_b32_e32 v64, 16, v50
	v_and_b32_e32 v65, 0xffff0000, v50
	v_lshlrev_b32_e32 v66, 16, v51
	v_and_b32_e32 v67, 0xffff0000, v51
	ds_write_b128 v151, v[60:63]
	ds_write_b128 v151, v[64:67] offset:16
.Lrc_skip:
	s_or_b64 exec, exec, s[26:27]
	s_branch .LBB0_423
